# S5 pass-1 items: B*u moved from packed-f32 VALU FMAs to f32 matrix-core products (v_mfma_f32_16x16x4_f32, f32 in / f32 accumulate); complex recurrence stays on the VALU in f32
# speedup vs baseline: 1.2641x; 1.0051x over previous
; __device__ __forceinline__ int otid() { int t = threadIdx.x; asm volatile("" : "+v"(t)); return t; }
; __device__ void phase_s5_pass1(CParams& p, int l, int item, char* smem) {
;   const int tid = otid(), lane = tid & 63, wid = tid >> 6;
;   int q = item >> 3, dir = (item >> 2) & 1, gq = item & 3;
;   int g = gq * 4 + wid;
;   float* us = (float*)smem + wid * 1024;
;   int tok0 = q * 64;
;   __syncthreads();
;   {
;     const float* src = p.zs5 + (size_t)(tok0 + lane) * 256 + g * 16;
; #pragma unroll
;     for (int i = 0; i < 4; i++) *(float4*)(us + lane * 16 + i * 4) = *(const float4*)(src + i * 4);
;   }
;   int pidx = ((l * 2 + dir) * 16 + g) * 64 + lane;
;   float2 A = p.Apar[pidx];
;   f32x2 bb[16];
; #pragma unroll
;   for (int cc = 0; cc < 16; cc++) {
;     float2 b = p.Bbar[(size_t)pidx * 16 + cc];
;     bb[cc] = f32x2{b.x, b.y};
;   }
;   __syncthreads();
;   float hr = 0.f, hi = 0.f;
;   for (int i = 0; i < 64; i++) {
;     int t = dir == 0 ? i : 63 - i;
;     float u[16];
; #pragma unroll
;     for (int k = 0; k < 4; k++) {
;       float4 uv = *(const float4*)(us + t * 16 + k * 4);
;       u[k * 4] = uv.x; u[k * 4 + 1] = uv.y; u[k * 4 + 2] = uv.z; u[k * 4 + 3] = uv.w;
;     }
;     f32x2 bu = {0.f, 0.f};
; #pragma unroll
;     for (int cc = 0; cc < 16; cc++) bu = __builtin_elementwise_fma(bb[cc], f32x2{u[cc], u[cc]}, bu);
.LBB0_379:
	s_cmpk_gt_i32 s29, 0x1ff
	s_mov_b64 s[26:27], -1
	s_mov_b32 s1, 0xffff0000
	s_mov_b32 s16, 0x8000
	s_cbranch_scc0 .LBB0_387
	s_cmpk_gt_u32 s29, 0x27f
	s_cbranch_scc0 .LBB0_384
	s_add_i32 s2, s29, 0xfffffd80
	v_readfirstlane_b32 s32, v147
	v_and_b32_e32 v32, 63, v147
	s_lshr_b32 s4, s2, 3
	s_lshr_b32 s10, s2, 2
	s_and_b32 s10, s10, 1
	s_and_b32 s17, s2, 3
	s_lshl_b32 s17, s17, 2
	s_lshr_b32 s32, s32, 6
	s_add_u32 s17, s17, s32
	s_lshl_b32 s0, s10, 4
	s_add_u32 s0, s0, s28
	s_add_u32 s0, s0, s17
	s_lshl_b32 s33, s0, 6
	s_lshl_b32 s0, s33, 3
	s_add_u32 s6, s48, s0
	s_addc_u32 s7, s49, 0
	s_lshl_b32 s0, s33, 7
	s_add_u32 s8, s50, s0
	s_addc_u32 s9, s51, 0
	s_lshl_b32 s0, s4, 16
	s_lshl_b32 s62, s17, 6
	s_add_u32 s0, s0, s62
	s_add_u32 s12, s42, s0
	s_addc_u32 s13, s43, 0
	s_lshl_b32 s0, s4, 1
	s_add_u32 s0, s0, s10
	s_lshl_b32 s0, s0, 4
	s_add_u32 s0, s0, s17
	s_lshl_b32 s0, s0, 9
	s_add_u32 s18, s20, s0
	s_addc_u32 s19, s21, 0
	s_lshl_b32 s93, s32, 14
	s_cmp_ge_u32 s32, 2
	s_cselect_b32 s0, 0x4000, 0
	s_add_u32 s93, s93, s0
	v_and_b32_e32 v33, 15, v32
	v_lshrrev_b32_e32 v34, 4, v32
	v_lshlrev_b32_e32 v38, 3, v32
	global_load_dwordx2 v[36:37], v38, s[6:7]
	v_lshlrev_b32_e32 v40, 7, v33
	v_lshl_add_u32 v40, v34, 5, v40
	v_add_u32_e32 v41, 0x1000, v40
	global_load_dwordx2 v[64:65], v40, s[8:9] offset:0
	global_load_dwordx2 v[66:67], v40, s[8:9] offset:8
	global_load_dwordx2 v[68:69], v40, s[8:9] offset:16
	global_load_dwordx2 v[70:71], v40, s[8:9] offset:24
	global_load_dwordx2 v[72:73], v40, s[8:9] offset:2048
	global_load_dwordx2 v[74:75], v40, s[8:9] offset:2056
	global_load_dwordx2 v[76:77], v40, s[8:9] offset:2064
	global_load_dwordx2 v[78:79], v40, s[8:9] offset:2072
	global_load_dwordx2 v[80:81], v41, s[8:9] offset:0
	global_load_dwordx2 v[82:83], v41, s[8:9] offset:8
	global_load_dwordx2 v[84:85], v41, s[8:9] offset:16
	global_load_dwordx2 v[86:87], v41, s[8:9] offset:24
	global_load_dwordx2 v[88:89], v41, s[8:9] offset:2048
	global_load_dwordx2 v[90:91], v41, s[8:9] offset:2056
	global_load_dwordx2 v[92:93], v41, s[8:9] offset:2064
	global_load_dwordx2 v[94:95], v41, s[8:9] offset:2072
	v_sub_u32_e32 v38, 63, v33
	s_mov_b32 s92, 0xffffc000
	s_cmp_eq_u32 s10, 0
	s_cselect_b64 vcc, -1, 0
	s_nop 1
	v_cndmask_b32_e32 v38, v38, v33, vcc
	v_lshlrev_b32_e32 v42, 10, v38
	v_lshl_add_u32 v42, v34, 4, v42
	s_cselect_b32 s92, 0x4000, s92
	global_load_dwordx4 v[96:99], v42, s[12:13]
	v_add_u32_e32 v42, s92, v42
	global_load_dwordx4 v[100:103], v42, s[12:13]
	v_add_u32_e32 v42, s92, v42
	global_load_dwordx4 v[104:107], v42, s[12:13]
	v_add_u32_e32 v42, s92, v42
	global_load_dwordx4 v[108:111], v42, s[12:13]
	v_lshlrev_b32_e32 v38, 11, v34
	v_lshl_add_u32 v38, v33, 3, v38
	v_add_u32_e32 v38, s93, v38
	v_add_u32_e32 v44, 0x0, v38
	v_add_u32_e32 v45, 0x200, v38
	v_add_u32_e32 v46, 0x400, v38
	v_add_u32_e32 v47, 0x600, v38
	v_add_u32_e32 v48, 0x2000, v38
	v_add_u32_e32 v49, 0x2200, v38
	v_add_u32_e32 v50, 0x2400, v38
	v_add_u32_e32 v51, 0x2600, v38
	v_lshlrev_b32_e32 v52, 3, v32
	v_add_u32_e32 v52, s93, v52
	v_mov_b32_e32 v54, 0
	v_mov_b32_e32 v55, 0
	s_barrier
	s_waitcnt vmcnt(3)
	v_mfma_f32_16x16x4_f32 v[0:3], v96, v64, 0
	v_mfma_f32_16x16x4_f32 v[4:7], v96, v65, 0
	v_mfma_f32_16x16x4_f32 v[8:11], v96, v72, 0
	v_mfma_f32_16x16x4_f32 v[12:15], v96, v73, 0
	v_mfma_f32_16x16x4_f32 v[16:19], v96, v80, 0
	v_mfma_f32_16x16x4_f32 v[20:23], v96, v81, 0
	v_mfma_f32_16x16x4_f32 v[24:27], v96, v88, 0
	v_mfma_f32_16x16x4_f32 v[28:31], v96, v89, 0
	v_mfma_f32_16x16x4_f32 v[0:3], v97, v66, v[0:3]
	v_mfma_f32_16x16x4_f32 v[4:7], v97, v67, v[4:7]
	v_mfma_f32_16x16x4_f32 v[8:11], v97, v74, v[8:11]
	v_mfma_f32_16x16x4_f32 v[12:15], v97, v75, v[12:15]
	v_mfma_f32_16x16x4_f32 v[16:19], v97, v82, v[16:19]
	v_mfma_f32_16x16x4_f32 v[20:23], v97, v83, v[20:23]
	v_mfma_f32_16x16x4_f32 v[24:27], v97, v90, v[24:27]
	v_mfma_f32_16x16x4_f32 v[28:31], v97, v91, v[28:31]
	v_mfma_f32_16x16x4_f32 v[0:3], v98, v68, v[0:3]
	v_mfma_f32_16x16x4_f32 v[4:7], v98, v69, v[4:7]
	v_mfma_f32_16x16x4_f32 v[8:11], v98, v76, v[8:11]
	v_mfma_f32_16x16x4_f32 v[12:15], v98, v77, v[12:15]
	v_mfma_f32_16x16x4_f32 v[16:19], v98, v84, v[16:19]
	v_mfma_f32_16x16x4_f32 v[20:23], v98, v85, v[20:23]
	v_mfma_f32_16x16x4_f32 v[24:27], v98, v92, v[24:27]
	v_mfma_f32_16x16x4_f32 v[28:31], v98, v93, v[28:31]
	v_mfma_f32_16x16x4_f32 v[0:3], v99, v70, v[0:3]
	v_mfma_f32_16x16x4_f32 v[4:7], v99, v71, v[4:7]
	v_mfma_f32_16x16x4_f32 v[8:11], v99, v78, v[8:11]
	v_mfma_f32_16x16x4_f32 v[12:15], v99, v79, v[12:15]
	v_mfma_f32_16x16x4_f32 v[16:19], v99, v86, v[16:19]
	v_mfma_f32_16x16x4_f32 v[20:23], v99, v87, v[20:23]
	v_mfma_f32_16x16x4_f32 v[24:27], v99, v94, v[24:27]
	v_mfma_f32_16x16x4_f32 v[28:31], v99, v95, v[28:31]
	s_nop 15
	s_nop 15
	ds_write2_b32 v44, v0, v4 offset0:0 offset1:1
	ds_write2_b32 v45, v1, v5 offset0:0 offset1:1
	ds_write2_b32 v46, v2, v6 offset0:0 offset1:1
	ds_write2_b32 v47, v3, v7 offset0:0 offset1:1
	ds_write2_b32 v44, v8, v12 offset0:32 offset1:33
	ds_write2_b32 v45, v9, v13 offset0:32 offset1:33
	ds_write2_b32 v46, v10, v14 offset0:32 offset1:33
	ds_write2_b32 v47, v11, v15 offset0:32 offset1:33
	ds_write2_b32 v44, v16, v20 offset0:64 offset1:65
	ds_write2_b32 v45, v17, v21 offset0:64 offset1:65
	ds_write2_b32 v46, v18, v22 offset0:64 offset1:65
	ds_write2_b32 v47, v19, v23 offset0:64 offset1:65
	ds_write2_b32 v44, v24, v28 offset0:96 offset1:97
	ds_write2_b32 v45, v25, v29 offset0:96 offset1:97
	ds_write2_b32 v46, v26, v30 offset0:96 offset1:97
	ds_write2_b32 v47, v27, v31 offset0:96 offset1:97
	ds_read_b64 v[0:1], v52 offset:0
	ds_read_b64 v[2:3], v52 offset:512
	ds_read_b64 v[4:5], v52 offset:1024
	ds_read_b64 v[6:7], v52 offset:1536
	ds_read_b64 v[8:9], v52 offset:2048
	ds_read_b64 v[10:11], v52 offset:2560
	ds_read_b64 v[12:13], v52 offset:3072
	ds_read_b64 v[14:15], v52 offset:3584
	ds_read_b64 v[16:17], v52 offset:4096
	ds_read_b64 v[18:19], v52 offset:4608
	ds_read_b64 v[20:21], v52 offset:5120
	ds_read_b64 v[22:23], v52 offset:5632
	ds_read_b64 v[24:25], v52 offset:6144
	ds_read_b64 v[26:27], v52 offset:6656
	ds_read_b64 v[28:29], v52 offset:7168
	ds_read_b64 v[30:31], v52 offset:7680
	s_waitcnt vmcnt(2)
; __device__ void phase_s5_pass1(CParams& p, int l, int item, char* smem) {
;     ...
;   for (int i = 0; i < 64; i++) {
;     int t = dir == 0 ? i : 63 - i;
;     float u[16];
; #pragma unroll
;     for (int k = 0; k < 4; k++) {
;       float4 uv = *(const float4*)(us + t * 16 + k * 4);
;       u[k * 4] = uv.x; u[k * 4 + 1] = uv.y; u[k * 4 + 2] = uv.z; u[k * 4 + 3] = uv.w;
;     }
;     f32x2 bu = {0.f, 0.f};
; #pragma unroll
;     for (int cc = 0; cc < 16; cc++) bu = __builtin_elementwise_fma(bb[cc], f32x2{u[cc], u[cc]}, bu);
;     float nr = A.x * hr - A.y * hi + bu[0];
;     float ni = A.x * hi + A.y * hr + bu[1];
;     hr = nr; hi = ni;
	s_waitcnt lgkmcnt(15)
	v_fma_f32 v58, v36, v54, v0
	v_fma_f32 v59, v36, v55, v1
	v_mfma_f32_16x16x4_f32 v[112:115], v100, v64, 0
	v_mfma_f32_16x16x4_f32 v[116:119], v100, v65, 0
	v_fma_f32 v56, -v37, v55, v58
	v_fma_f32 v57, v37, v54, v59
	s_waitcnt lgkmcnt(14)
	v_fma_f32 v58, v36, v56, v2
	v_fma_f32 v59, v36, v57, v3
	v_mfma_f32_16x16x4_f32 v[120:123], v100, v72, 0
	v_mfma_f32_16x16x4_f32 v[124:127], v100, v73, 0
	v_fma_f32 v54, -v37, v57, v58
	v_fma_f32 v55, v37, v56, v59
	s_waitcnt lgkmcnt(13)
	v_fma_f32 v58, v36, v54, v4
	v_fma_f32 v59, v36, v55, v5
	v_mfma_f32_16x16x4_f32 v[128:131], v100, v80, 0
	v_mfma_f32_16x16x4_f32 v[132:135], v100, v81, 0
	v_fma_f32 v56, -v37, v55, v58
	v_fma_f32 v57, v37, v54, v59
	s_waitcnt lgkmcnt(12)
	v_fma_f32 v58, v36, v56, v6
	v_fma_f32 v59, v36, v57, v7
	v_mfma_f32_16x16x4_f32 v[136:139], v100, v88, 0
	v_mfma_f32_16x16x4_f32 v[140:143], v100, v89, 0
	v_fma_f32 v54, -v37, v57, v58
	v_fma_f32 v55, v37, v56, v59
	s_waitcnt lgkmcnt(11)
	v_fma_f32 v58, v36, v54, v8
	v_fma_f32 v59, v36, v55, v9
	v_mfma_f32_16x16x4_f32 v[112:115], v101, v66, v[112:115]
	v_mfma_f32_16x16x4_f32 v[116:119], v101, v67, v[116:119]
	v_fma_f32 v56, -v37, v55, v58
	v_fma_f32 v57, v37, v54, v59
	s_waitcnt lgkmcnt(10)
	v_fma_f32 v58, v36, v56, v10
	v_fma_f32 v59, v36, v57, v11
	v_mfma_f32_16x16x4_f32 v[120:123], v101, v74, v[120:123]
	v_mfma_f32_16x16x4_f32 v[124:127], v101, v75, v[124:127]
	v_fma_f32 v54, -v37, v57, v58
	v_fma_f32 v55, v37, v56, v59
	s_waitcnt lgkmcnt(9)
	v_fma_f32 v58, v36, v54, v12
	v_fma_f32 v59, v36, v55, v13
	v_mfma_f32_16x16x4_f32 v[128:131], v101, v82, v[128:131]
	v_mfma_f32_16x16x4_f32 v[132:135], v101, v83, v[132:135]
	v_fma_f32 v56, -v37, v55, v58
	v_fma_f32 v57, v37, v54, v59
	s_waitcnt lgkmcnt(8)
	v_fma_f32 v58, v36, v56, v14
	v_fma_f32 v59, v36, v57, v15
	v_mfma_f32_16x16x4_f32 v[136:139], v101, v90, v[136:139]
	v_mfma_f32_16x16x4_f32 v[140:143], v101, v91, v[140:143]
	v_fma_f32 v54, -v37, v57, v58
	v_fma_f32 v55, v37, v56, v59
	s_waitcnt lgkmcnt(7)
	v_fma_f32 v58, v36, v54, v16
	v_fma_f32 v59, v36, v55, v17
	v_mfma_f32_16x16x4_f32 v[112:115], v102, v68, v[112:115]
	v_mfma_f32_16x16x4_f32 v[116:119], v102, v69, v[116:119]
	v_fma_f32 v56, -v37, v55, v58
	v_fma_f32 v57, v37, v54, v59
	s_waitcnt lgkmcnt(6)
	v_fma_f32 v58, v36, v56, v18
	v_fma_f32 v59, v36, v57, v19
	v_mfma_f32_16x16x4_f32 v[120:123], v102, v76, v[120:123]
	v_mfma_f32_16x16x4_f32 v[124:127], v102, v77, v[124:127]
	v_fma_f32 v54, -v37, v57, v58
	v_fma_f32 v55, v37, v56, v59
	s_waitcnt lgkmcnt(5)
	v_fma_f32 v58, v36, v54, v20
	v_fma_f32 v59, v36, v55, v21
	v_mfma_f32_16x16x4_f32 v[128:131], v102, v84, v[128:131]
	v_mfma_f32_16x16x4_f32 v[132:135], v102, v85, v[132:135]
	v_fma_f32 v56, -v37, v55, v58
	v_fma_f32 v57, v37, v54, v59
	s_waitcnt lgkmcnt(4)
	v_fma_f32 v58, v36, v56, v22
	v_fma_f32 v59, v36, v57, v23
	v_mfma_f32_16x16x4_f32 v[136:139], v102, v92, v[136:139]
	v_mfma_f32_16x16x4_f32 v[140:143], v102, v93, v[140:143]
	v_fma_f32 v54, -v37, v57, v58
	v_fma_f32 v55, v37, v56, v59
	s_waitcnt lgkmcnt(3)
	v_fma_f32 v58, v36, v54, v24
	v_fma_f32 v59, v36, v55, v25
	v_mfma_f32_16x16x4_f32 v[112:115], v103, v70, v[112:115]
	v_mfma_f32_16x16x4_f32 v[116:119], v103, v71, v[116:119]
	v_fma_f32 v56, -v37, v55, v58
	v_fma_f32 v57, v37, v54, v59
	s_waitcnt lgkmcnt(2)
	v_fma_f32 v58, v36, v56, v26
	v_fma_f32 v59, v36, v57, v27
	v_mfma_f32_16x16x4_f32 v[120:123], v103, v78, v[120:123]
	v_mfma_f32_16x16x4_f32 v[124:127], v103, v79, v[124:127]
	v_fma_f32 v54, -v37, v57, v58
	v_fma_f32 v55, v37, v56, v59
	s_waitcnt lgkmcnt(1)
	v_fma_f32 v58, v36, v54, v28
	v_fma_f32 v59, v36, v55, v29
	v_mfma_f32_16x16x4_f32 v[128:131], v103, v86, v[128:131]
	v_mfma_f32_16x16x4_f32 v[132:135], v103, v87, v[132:135]
	v_fma_f32 v56, -v37, v55, v58
	v_fma_f32 v57, v37, v54, v59
	s_waitcnt lgkmcnt(0)
	v_fma_f32 v58, v36, v56, v30
	v_fma_f32 v59, v36, v57, v31
	v_mfma_f32_16x16x4_f32 v[136:139], v103, v94, v[136:139]
	v_mfma_f32_16x16x4_f32 v[140:143], v103, v95, v[140:143]
	v_fma_f32 v54, -v37, v57, v58
	v_fma_f32 v55, v37, v56, v59
	s_nop 15
	s_nop 15
	ds_write2_b32 v48, v112, v116 offset0:0 offset1:1
	ds_write2_b32 v49, v113, v117 offset0:0 offset1:1
	ds_write2_b32 v50, v114, v118 offset0:0 offset1:1
	ds_write2_b32 v51, v115, v119 offset0:0 offset1:1
	ds_write2_b32 v48, v120, v124 offset0:32 offset1:33
	ds_write2_b32 v49, v121, v125 offset0:32 offset1:33
	ds_write2_b32 v50, v122, v126 offset0:32 offset1:33
	ds_write2_b32 v51, v123, v127 offset0:32 offset1:33
	ds_write2_b32 v48, v128, v132 offset0:64 offset1:65
	ds_write2_b32 v49, v129, v133 offset0:64 offset1:65
	ds_write2_b32 v50, v130, v134 offset0:64 offset1:65
	ds_write2_b32 v51, v131, v135 offset0:64 offset1:65
	ds_write2_b32 v48, v136, v140 offset0:96 offset1:97
	ds_write2_b32 v49, v137, v141 offset0:96 offset1:97
	ds_write2_b32 v50, v138, v142 offset0:96 offset1:97
	ds_write2_b32 v51, v139, v143 offset0:96 offset1:97
	ds_read_b64 v[112:113], v52 offset:8192
	ds_read_b64 v[114:115], v52 offset:8704
	ds_read_b64 v[116:117], v52 offset:9216
	ds_read_b64 v[118:119], v52 offset:9728
	ds_read_b64 v[120:121], v52 offset:10240
	ds_read_b64 v[122:123], v52 offset:10752
	ds_read_b64 v[124:125], v52 offset:11264
	ds_read_b64 v[126:127], v52 offset:11776
	ds_read_b64 v[128:129], v52 offset:12288
	ds_read_b64 v[130:131], v52 offset:12800
	ds_read_b64 v[132:133], v52 offset:13312
	ds_read_b64 v[134:135], v52 offset:13824
	ds_read_b64 v[136:137], v52 offset:14336
	ds_read_b64 v[138:139], v52 offset:14848
	ds_read_b64 v[140:141], v52 offset:15360
	ds_read_b64 v[142:143], v52 offset:15872
	s_waitcnt vmcnt(1)
	s_waitcnt lgkmcnt(15)
; __device__ void phase_s5_pass1(CParams& p, int l, int item, char* smem) {
;     ...
;   for (int i = 0; i < 64; i++) {
;     int t = dir == 0 ? i : 63 - i;
;     float u[16];
; #pragma unroll
;     for (int k = 0; k < 4; k++) {
;       float4 uv = *(const float4*)(us + t * 16 + k * 4);
;       u[k * 4] = uv.x; u[k * 4 + 1] = uv.y; u[k * 4 + 2] = uv.z; u[k * 4 + 3] = uv.w;
;     }
;     f32x2 bu = {0.f, 0.f};
; #pragma unroll
;     for (int cc = 0; cc < 16; cc++) bu = __builtin_elementwise_fma(bb[cc], f32x2{u[cc], u[cc]}, bu);
;     float nr = A.x * hr - A.y * hi + bu[0];
;     float ni = A.x * hi + A.y * hr + bu[1];
;     hr = nr; hi = ni;
	v_fma_f32 v58, v36, v54, v112
	v_fma_f32 v59, v36, v55, v113
	v_mfma_f32_16x16x4_f32 v[0:3], v104, v64, 0
	v_mfma_f32_16x16x4_f32 v[4:7], v104, v65, 0
	v_fma_f32 v56, -v37, v55, v58
	v_fma_f32 v57, v37, v54, v59
	s_waitcnt lgkmcnt(14)
	v_fma_f32 v58, v36, v56, v114
	v_fma_f32 v59, v36, v57, v115
	v_mfma_f32_16x16x4_f32 v[8:11], v104, v72, 0
	v_mfma_f32_16x16x4_f32 v[12:15], v104, v73, 0
	v_fma_f32 v54, -v37, v57, v58
	v_fma_f32 v55, v37, v56, v59
	s_waitcnt lgkmcnt(13)
	v_fma_f32 v58, v36, v54, v116
	v_fma_f32 v59, v36, v55, v117
	v_mfma_f32_16x16x4_f32 v[16:19], v104, v80, 0
	v_mfma_f32_16x16x4_f32 v[20:23], v104, v81, 0
	v_fma_f32 v56, -v37, v55, v58
	v_fma_f32 v57, v37, v54, v59
	s_waitcnt lgkmcnt(12)
	v_fma_f32 v58, v36, v56, v118
	v_fma_f32 v59, v36, v57, v119
	v_mfma_f32_16x16x4_f32 v[24:27], v104, v88, 0
	v_mfma_f32_16x16x4_f32 v[28:31], v104, v89, 0
	v_fma_f32 v54, -v37, v57, v58
	v_fma_f32 v55, v37, v56, v59
	s_waitcnt lgkmcnt(11)
	v_fma_f32 v58, v36, v54, v120
	v_fma_f32 v59, v36, v55, v121
	v_mfma_f32_16x16x4_f32 v[0:3], v105, v66, v[0:3]
	v_mfma_f32_16x16x4_f32 v[4:7], v105, v67, v[4:7]
	v_fma_f32 v56, -v37, v55, v58
	v_fma_f32 v57, v37, v54, v59
	s_waitcnt lgkmcnt(10)
	v_fma_f32 v58, v36, v56, v122
	v_fma_f32 v59, v36, v57, v123
	v_mfma_f32_16x16x4_f32 v[8:11], v105, v74, v[8:11]
	v_mfma_f32_16x16x4_f32 v[12:15], v105, v75, v[12:15]
	v_fma_f32 v54, -v37, v57, v58
	v_fma_f32 v55, v37, v56, v59
	s_waitcnt lgkmcnt(9)
	v_fma_f32 v58, v36, v54, v124
	v_fma_f32 v59, v36, v55, v125
	v_mfma_f32_16x16x4_f32 v[16:19], v105, v82, v[16:19]
	v_mfma_f32_16x16x4_f32 v[20:23], v105, v83, v[20:23]
	v_fma_f32 v56, -v37, v55, v58
	v_fma_f32 v57, v37, v54, v59
	s_waitcnt lgkmcnt(8)
	v_fma_f32 v58, v36, v56, v126
	v_fma_f32 v59, v36, v57, v127
	v_mfma_f32_16x16x4_f32 v[24:27], v105, v90, v[24:27]
	v_mfma_f32_16x16x4_f32 v[28:31], v105, v91, v[28:31]
	v_fma_f32 v54, -v37, v57, v58
	v_fma_f32 v55, v37, v56, v59
	s_waitcnt lgkmcnt(7)
	v_fma_f32 v58, v36, v54, v128
	v_fma_f32 v59, v36, v55, v129
	v_mfma_f32_16x16x4_f32 v[0:3], v106, v68, v[0:3]
	v_mfma_f32_16x16x4_f32 v[4:7], v106, v69, v[4:7]
	v_fma_f32 v56, -v37, v55, v58
	v_fma_f32 v57, v37, v54, v59
	s_waitcnt lgkmcnt(6)
	v_fma_f32 v58, v36, v56, v130
	v_fma_f32 v59, v36, v57, v131
	v_mfma_f32_16x16x4_f32 v[8:11], v106, v76, v[8:11]
	v_mfma_f32_16x16x4_f32 v[12:15], v106, v77, v[12:15]
	v_fma_f32 v54, -v37, v57, v58
	v_fma_f32 v55, v37, v56, v59
	s_waitcnt lgkmcnt(5)
	v_fma_f32 v58, v36, v54, v132
	v_fma_f32 v59, v36, v55, v133
	v_mfma_f32_16x16x4_f32 v[16:19], v106, v84, v[16:19]
	v_mfma_f32_16x16x4_f32 v[20:23], v106, v85, v[20:23]
	v_fma_f32 v56, -v37, v55, v58
	v_fma_f32 v57, v37, v54, v59
	s_waitcnt lgkmcnt(4)
	v_fma_f32 v58, v36, v56, v134
	v_fma_f32 v59, v36, v57, v135
	v_mfma_f32_16x16x4_f32 v[24:27], v106, v92, v[24:27]
	v_mfma_f32_16x16x4_f32 v[28:31], v106, v93, v[28:31]
	v_fma_f32 v54, -v37, v57, v58
	v_fma_f32 v55, v37, v56, v59
	s_waitcnt lgkmcnt(3)
	v_fma_f32 v58, v36, v54, v136
	v_fma_f32 v59, v36, v55, v137
	v_mfma_f32_16x16x4_f32 v[0:3], v107, v70, v[0:3]
	v_mfma_f32_16x16x4_f32 v[4:7], v107, v71, v[4:7]
	v_fma_f32 v56, -v37, v55, v58
	v_fma_f32 v57, v37, v54, v59
	s_waitcnt lgkmcnt(2)
	v_fma_f32 v58, v36, v56, v138
	v_fma_f32 v59, v36, v57, v139
	v_mfma_f32_16x16x4_f32 v[8:11], v107, v78, v[8:11]
	v_mfma_f32_16x16x4_f32 v[12:15], v107, v79, v[12:15]
	v_fma_f32 v54, -v37, v57, v58
	v_fma_f32 v55, v37, v56, v59
	s_waitcnt lgkmcnt(1)
	v_fma_f32 v58, v36, v54, v140
	v_fma_f32 v59, v36, v55, v141
	v_mfma_f32_16x16x4_f32 v[16:19], v107, v86, v[16:19]
	v_mfma_f32_16x16x4_f32 v[20:23], v107, v87, v[20:23]
	v_fma_f32 v56, -v37, v55, v58
	v_fma_f32 v57, v37, v54, v59
	s_waitcnt lgkmcnt(0)
	v_fma_f32 v58, v36, v56, v142
	v_fma_f32 v59, v36, v57, v143
	v_mfma_f32_16x16x4_f32 v[24:27], v107, v94, v[24:27]
	v_mfma_f32_16x16x4_f32 v[28:31], v107, v95, v[28:31]
	v_fma_f32 v54, -v37, v57, v58
	v_fma_f32 v55, v37, v56, v59
	s_nop 15
	s_nop 15
	ds_write2_b32 v44, v0, v4 offset0:0 offset1:1
	ds_write2_b32 v45, v1, v5 offset0:0 offset1:1
	ds_write2_b32 v46, v2, v6 offset0:0 offset1:1
	ds_write2_b32 v47, v3, v7 offset0:0 offset1:1
	ds_write2_b32 v44, v8, v12 offset0:32 offset1:33
	ds_write2_b32 v45, v9, v13 offset0:32 offset1:33
	ds_write2_b32 v46, v10, v14 offset0:32 offset1:33
	ds_write2_b32 v47, v11, v15 offset0:32 offset1:33
	ds_write2_b32 v44, v16, v20 offset0:64 offset1:65
	ds_write2_b32 v45, v17, v21 offset0:64 offset1:65
	ds_write2_b32 v46, v18, v22 offset0:64 offset1:65
	ds_write2_b32 v47, v19, v23 offset0:64 offset1:65
	ds_write2_b32 v44, v24, v28 offset0:96 offset1:97
	ds_write2_b32 v45, v25, v29 offset0:96 offset1:97
	ds_write2_b32 v46, v26, v30 offset0:96 offset1:97
	ds_write2_b32 v47, v27, v31 offset0:96 offset1:97
	ds_read_b64 v[0:1], v52 offset:0
	ds_read_b64 v[2:3], v52 offset:512
	ds_read_b64 v[4:5], v52 offset:1024
	ds_read_b64 v[6:7], v52 offset:1536
	ds_read_b64 v[8:9], v52 offset:2048
	ds_read_b64 v[10:11], v52 offset:2560
	ds_read_b64 v[12:13], v52 offset:3072
	ds_read_b64 v[14:15], v52 offset:3584
	ds_read_b64 v[16:17], v52 offset:4096
	ds_read_b64 v[18:19], v52 offset:4608
	ds_read_b64 v[20:21], v52 offset:5120
	ds_read_b64 v[22:23], v52 offset:5632
	ds_read_b64 v[24:25], v52 offset:6144
	ds_read_b64 v[26:27], v52 offset:6656
	ds_read_b64 v[28:29], v52 offset:7168
	ds_read_b64 v[30:31], v52 offset:7680
	s_waitcnt vmcnt(0)
	s_waitcnt lgkmcnt(15)
	v_fma_f32 v58, v36, v54, v0
	v_fma_f32 v59, v36, v55, v1
	v_mfma_f32_16x16x4_f32 v[112:115], v108, v64, 0
	v_mfma_f32_16x16x4_f32 v[116:119], v108, v65, 0
	v_fma_f32 v56, -v37, v55, v58
	v_fma_f32 v57, v37, v54, v59
	s_waitcnt lgkmcnt(14)
; __device__ void phase_s5_pass1(CParams& p, int l, int item, char* smem) {
;     ...
;   for (int i = 0; i < 64; i++) {
;     int t = dir == 0 ? i : 63 - i;
;     float u[16];
; #pragma unroll
;     for (int k = 0; k < 4; k++) {
;       float4 uv = *(const float4*)(us + t * 16 + k * 4);
;       u[k * 4] = uv.x; u[k * 4 + 1] = uv.y; u[k * 4 + 2] = uv.z; u[k * 4 + 3] = uv.w;
;     }
;     f32x2 bu = {0.f, 0.f};
; #pragma unroll
;     for (int cc = 0; cc < 16; cc++) bu = __builtin_elementwise_fma(bb[cc], f32x2{u[cc], u[cc]}, bu);
;     float nr = A.x * hr - A.y * hi + bu[0];
;     float ni = A.x * hi + A.y * hr + bu[1];
;     hr = nr; hi = ni;
	v_fma_f32 v58, v36, v56, v2
	v_fma_f32 v59, v36, v57, v3
	v_mfma_f32_16x16x4_f32 v[120:123], v108, v72, 0
	v_mfma_f32_16x16x4_f32 v[124:127], v108, v73, 0
	v_fma_f32 v54, -v37, v57, v58
	v_fma_f32 v55, v37, v56, v59
	s_waitcnt lgkmcnt(13)
	v_fma_f32 v58, v36, v54, v4
	v_fma_f32 v59, v36, v55, v5
	v_mfma_f32_16x16x4_f32 v[128:131], v108, v80, 0
	v_mfma_f32_16x16x4_f32 v[132:135], v108, v81, 0
	v_fma_f32 v56, -v37, v55, v58
	v_fma_f32 v57, v37, v54, v59
	s_waitcnt lgkmcnt(12)
	v_fma_f32 v58, v36, v56, v6
	v_fma_f32 v59, v36, v57, v7
	v_mfma_f32_16x16x4_f32 v[136:139], v108, v88, 0
	v_mfma_f32_16x16x4_f32 v[140:143], v108, v89, 0
	v_fma_f32 v54, -v37, v57, v58
	v_fma_f32 v55, v37, v56, v59
	s_waitcnt lgkmcnt(11)
	v_fma_f32 v58, v36, v54, v8
	v_fma_f32 v59, v36, v55, v9
	v_mfma_f32_16x16x4_f32 v[112:115], v109, v66, v[112:115]
	v_mfma_f32_16x16x4_f32 v[116:119], v109, v67, v[116:119]
	v_fma_f32 v56, -v37, v55, v58
	v_fma_f32 v57, v37, v54, v59
	s_waitcnt lgkmcnt(10)
	v_fma_f32 v58, v36, v56, v10
	v_fma_f32 v59, v36, v57, v11
	v_mfma_f32_16x16x4_f32 v[120:123], v109, v74, v[120:123]
	v_mfma_f32_16x16x4_f32 v[124:127], v109, v75, v[124:127]
	v_fma_f32 v54, -v37, v57, v58
	v_fma_f32 v55, v37, v56, v59
	s_waitcnt lgkmcnt(9)
	v_fma_f32 v58, v36, v54, v12
	v_fma_f32 v59, v36, v55, v13
	v_mfma_f32_16x16x4_f32 v[128:131], v109, v82, v[128:131]
	v_mfma_f32_16x16x4_f32 v[132:135], v109, v83, v[132:135]
	v_fma_f32 v56, -v37, v55, v58
	v_fma_f32 v57, v37, v54, v59
	s_waitcnt lgkmcnt(8)
	v_fma_f32 v58, v36, v56, v14
	v_fma_f32 v59, v36, v57, v15
	v_mfma_f32_16x16x4_f32 v[136:139], v109, v90, v[136:139]
	v_mfma_f32_16x16x4_f32 v[140:143], v109, v91, v[140:143]
	v_fma_f32 v54, -v37, v57, v58
	v_fma_f32 v55, v37, v56, v59
	s_waitcnt lgkmcnt(7)
	v_fma_f32 v58, v36, v54, v16
	v_fma_f32 v59, v36, v55, v17
	v_mfma_f32_16x16x4_f32 v[112:115], v110, v68, v[112:115]
	v_mfma_f32_16x16x4_f32 v[116:119], v110, v69, v[116:119]
	v_fma_f32 v56, -v37, v55, v58
	v_fma_f32 v57, v37, v54, v59
	s_waitcnt lgkmcnt(6)
	v_fma_f32 v58, v36, v56, v18
	v_fma_f32 v59, v36, v57, v19
	v_mfma_f32_16x16x4_f32 v[120:123], v110, v76, v[120:123]
	v_mfma_f32_16x16x4_f32 v[124:127], v110, v77, v[124:127]
	v_fma_f32 v54, -v37, v57, v58
	v_fma_f32 v55, v37, v56, v59
	s_waitcnt lgkmcnt(5)
	v_fma_f32 v58, v36, v54, v20
	v_fma_f32 v59, v36, v55, v21
	v_mfma_f32_16x16x4_f32 v[128:131], v110, v84, v[128:131]
	v_mfma_f32_16x16x4_f32 v[132:135], v110, v85, v[132:135]
	v_fma_f32 v56, -v37, v55, v58
	v_fma_f32 v57, v37, v54, v59
	s_waitcnt lgkmcnt(4)
	v_fma_f32 v58, v36, v56, v22
	v_fma_f32 v59, v36, v57, v23
	v_mfma_f32_16x16x4_f32 v[136:139], v110, v92, v[136:139]
	v_mfma_f32_16x16x4_f32 v[140:143], v110, v93, v[140:143]
	v_fma_f32 v54, -v37, v57, v58
	v_fma_f32 v55, v37, v56, v59
	s_waitcnt lgkmcnt(3)
	v_fma_f32 v58, v36, v54, v24
	v_fma_f32 v59, v36, v55, v25
	v_mfma_f32_16x16x4_f32 v[112:115], v111, v70, v[112:115]
	v_mfma_f32_16x16x4_f32 v[116:119], v111, v71, v[116:119]
	v_fma_f32 v56, -v37, v55, v58
	v_fma_f32 v57, v37, v54, v59
	s_waitcnt lgkmcnt(2)
	v_fma_f32 v58, v36, v56, v26
	v_fma_f32 v59, v36, v57, v27
	v_mfma_f32_16x16x4_f32 v[120:123], v111, v78, v[120:123]
	v_mfma_f32_16x16x4_f32 v[124:127], v111, v79, v[124:127]
	v_fma_f32 v54, -v37, v57, v58
	v_fma_f32 v55, v37, v56, v59
	s_waitcnt lgkmcnt(1)
	v_fma_f32 v58, v36, v54, v28
	v_fma_f32 v59, v36, v55, v29
	v_mfma_f32_16x16x4_f32 v[128:131], v111, v86, v[128:131]
	v_mfma_f32_16x16x4_f32 v[132:135], v111, v87, v[132:135]
	v_fma_f32 v56, -v37, v55, v58
	v_fma_f32 v57, v37, v54, v59
	s_waitcnt lgkmcnt(0)
; __device__ void phase_s5_pass1(CParams& p, int l, int item, char* smem) {
;     ...
;   for (int i = 0; i < 64; i++) {
;     int t = dir == 0 ? i : 63 - i;
;     float u[16];
; #pragma unroll
;     for (int k = 0; k < 4; k++) {
;       float4 uv = *(const float4*)(us + t * 16 + k * 4);
;       u[k * 4] = uv.x; u[k * 4 + 1] = uv.y; u[k * 4 + 2] = uv.z; u[k * 4 + 3] = uv.w;
;     }
;     f32x2 bu = {0.f, 0.f};
; #pragma unroll
;     for (int cc = 0; cc < 16; cc++) bu = __builtin_elementwise_fma(bb[cc], f32x2{u[cc], u[cc]}, bu);
;     float nr = A.x * hr - A.y * hi + bu[0];
;     float ni = A.x * hi + A.y * hr + bu[1];
;     hr = nr; hi = ni;
;   }
;   p.E[(((size_t)q * 2 + dir) * 16 + g) * 64 + lane] = make_float2(hr, hi);
	v_fma_f32 v58, v36, v56, v30
	v_fma_f32 v59, v36, v57, v31
	v_mfma_f32_16x16x4_f32 v[136:139], v111, v94, v[136:139]
	v_mfma_f32_16x16x4_f32 v[140:143], v111, v95, v[140:143]
	v_fma_f32 v54, -v37, v57, v58
	v_fma_f32 v55, v37, v56, v59
	s_nop 15
	s_nop 15
	ds_write2_b32 v48, v112, v116 offset0:0 offset1:1
	ds_write2_b32 v49, v113, v117 offset0:0 offset1:1
	ds_write2_b32 v50, v114, v118 offset0:0 offset1:1
	ds_write2_b32 v51, v115, v119 offset0:0 offset1:1
	ds_write2_b32 v48, v120, v124 offset0:32 offset1:33
	ds_write2_b32 v49, v121, v125 offset0:32 offset1:33
	ds_write2_b32 v50, v122, v126 offset0:32 offset1:33
	ds_write2_b32 v51, v123, v127 offset0:32 offset1:33
	ds_write2_b32 v48, v128, v132 offset0:64 offset1:65
	ds_write2_b32 v49, v129, v133 offset0:64 offset1:65
	ds_write2_b32 v50, v130, v134 offset0:64 offset1:65
	ds_write2_b32 v51, v131, v135 offset0:64 offset1:65
	ds_write2_b32 v48, v136, v140 offset0:96 offset1:97
	ds_write2_b32 v49, v137, v141 offset0:96 offset1:97
	ds_write2_b32 v50, v138, v142 offset0:96 offset1:97
	ds_write2_b32 v51, v139, v143 offset0:96 offset1:97
	ds_read_b64 v[112:113], v52 offset:8192
	ds_read_b64 v[114:115], v52 offset:8704
	ds_read_b64 v[116:117], v52 offset:9216
	ds_read_b64 v[118:119], v52 offset:9728
	ds_read_b64 v[120:121], v52 offset:10240
	ds_read_b64 v[122:123], v52 offset:10752
	ds_read_b64 v[124:125], v52 offset:11264
	ds_read_b64 v[126:127], v52 offset:11776
	ds_read_b64 v[128:129], v52 offset:12288
	ds_read_b64 v[130:131], v52 offset:12800
	ds_read_b64 v[132:133], v52 offset:13312
	ds_read_b64 v[134:135], v52 offset:13824
	ds_read_b64 v[136:137], v52 offset:14336
	ds_read_b64 v[138:139], v52 offset:14848
	ds_read_b64 v[140:141], v52 offset:15360
	ds_read_b64 v[142:143], v52 offset:15872
	s_waitcnt lgkmcnt(15)
	v_fma_f32 v58, v36, v54, v112
	v_fma_f32 v59, v36, v55, v113
	v_fma_f32 v56, -v37, v55, v58
	v_fma_f32 v57, v37, v54, v59
	s_waitcnt lgkmcnt(14)
	v_fma_f32 v58, v36, v56, v114
	v_fma_f32 v59, v36, v57, v115
	v_fma_f32 v54, -v37, v57, v58
	v_fma_f32 v55, v37, v56, v59
	s_waitcnt lgkmcnt(13)
	v_fma_f32 v58, v36, v54, v116
	v_fma_f32 v59, v36, v55, v117
	v_fma_f32 v56, -v37, v55, v58
	v_fma_f32 v57, v37, v54, v59
	s_waitcnt lgkmcnt(12)
	v_fma_f32 v58, v36, v56, v118
	v_fma_f32 v59, v36, v57, v119
	v_fma_f32 v54, -v37, v57, v58
	v_fma_f32 v55, v37, v56, v59
	s_waitcnt lgkmcnt(11)
	v_fma_f32 v58, v36, v54, v120
	v_fma_f32 v59, v36, v55, v121
	v_fma_f32 v56, -v37, v55, v58
	v_fma_f32 v57, v37, v54, v59
	s_waitcnt lgkmcnt(10)
	v_fma_f32 v58, v36, v56, v122
	v_fma_f32 v59, v36, v57, v123
	v_fma_f32 v54, -v37, v57, v58
	v_fma_f32 v55, v37, v56, v59
	s_waitcnt lgkmcnt(9)
	v_fma_f32 v58, v36, v54, v124
	v_fma_f32 v59, v36, v55, v125
	v_fma_f32 v56, -v37, v55, v58
	v_fma_f32 v57, v37, v54, v59
	s_waitcnt lgkmcnt(8)
	v_fma_f32 v58, v36, v56, v126
	v_fma_f32 v59, v36, v57, v127
	v_fma_f32 v54, -v37, v57, v58
	v_fma_f32 v55, v37, v56, v59
	s_waitcnt lgkmcnt(7)
	v_fma_f32 v58, v36, v54, v128
	v_fma_f32 v59, v36, v55, v129
	v_fma_f32 v56, -v37, v55, v58
	v_fma_f32 v57, v37, v54, v59
	s_waitcnt lgkmcnt(6)
	v_fma_f32 v58, v36, v56, v130
	v_fma_f32 v59, v36, v57, v131
	v_fma_f32 v54, -v37, v57, v58
	v_fma_f32 v55, v37, v56, v59
	s_waitcnt lgkmcnt(5)
	v_fma_f32 v58, v36, v54, v132
	v_fma_f32 v59, v36, v55, v133
	v_fma_f32 v56, -v37, v55, v58
	v_fma_f32 v57, v37, v54, v59
	s_waitcnt lgkmcnt(4)
	v_fma_f32 v58, v36, v56, v134
	v_fma_f32 v59, v36, v57, v135
	v_fma_f32 v54, -v37, v57, v58
	v_fma_f32 v55, v37, v56, v59
	s_waitcnt lgkmcnt(3)
	v_fma_f32 v58, v36, v54, v136
	v_fma_f32 v59, v36, v55, v137
	v_fma_f32 v56, -v37, v55, v58
	v_fma_f32 v57, v37, v54, v59
	s_waitcnt lgkmcnt(2)
	v_fma_f32 v58, v36, v56, v138
	v_fma_f32 v59, v36, v57, v139
	v_fma_f32 v54, -v37, v57, v58
	v_fma_f32 v55, v37, v56, v59
	s_waitcnt lgkmcnt(1)
	v_fma_f32 v58, v36, v54, v140
	v_fma_f32 v59, v36, v55, v141
	v_fma_f32 v56, -v37, v55, v58
	v_fma_f32 v57, v37, v54, v59
	s_waitcnt lgkmcnt(0)
	v_fma_f32 v58, v36, v56, v142
	v_fma_f32 v59, v36, v57, v143
	v_fma_f32 v54, -v37, v57, v58
	v_fma_f32 v55, v37, v56, v59
	v_lshlrev_b32_e32 v38, 3, v32
	global_store_dwordx2 v38, v[54:55], s[18:19]
	s_waitcnt lgkmcnt(0)
	s_barrier
	s_mov_b64 s[26:27], 0
	s_movk_i32 s0, 0x4000
